# latent attention: next tile's first-half exps moved from the serial loop head to the loop bottom (overlap the LDS drain and barrier wait)
# baseline (speedup 1.0000x reference)
.LBB0_208:
	global_load_dwordx4 v[152:155], v167, s[48:49]
	global_load_dwordx4 v[156:159], v167, s[4:5]
	s_cmp_lt_u32 s41, 34
	s_cselect_b64 s[0:1], -1, 0
	s_cmp_gt_u32 s41, 33
	s_nop 3
	v_exp_f32_e32 v179, v80
	v_exp_f32_e32 v180, v81
	v_exp_f32_e32 v181, v82
	v_exp_f32_e32 v182, v83
	v_exp_f32_e32 v183, v84
	v_exp_f32_e32 v184, v85
	v_exp_f32_e32 v185, v86
	v_exp_f32_e32 v186, v87
	v_exp_f32_e32 v187, v88
	v_exp_f32_e32 v188, v89
	v_exp_f32_e32 v189, v90
	v_exp_f32_e32 v190, v91
	v_exp_f32_e32 v191, v92
	v_exp_f32_e32 v194, v93
	v_exp_f32_e32 v195, v94
	v_exp_f32_e32 v196, v95
	s_cbranch_scc1 .LBB0_210
	global_load_dwordx4 v[128:131], v178, s[2:3]
	global_load_dwordx4 v[132:135], v178, s[62:63]
.LBB0_210:
	s_add_i32 s71, s64, 0x4000
	s_and_b32 s9, s71, 0x4000
	v_add_u32_e32 v222, s9, v177
	v_add_u32_e32 v197, v222, v176
	v_add_u32_e32 v202, v222, v175
	v_add_u32_e32 v203, v222, v173
	v_add_u32_e32 v204, v222, v171
	ds_read_b128 v[214:217], v197 offset:4096
	ds_read_b128 v[218:221], v202 offset:4096
	ds_read_b128 v[246:249], v203 offset:4096
	ds_read_b128 v[236:239], v204 offset:4096
	v_add_u32_e32 v205, s9, v174
	v_add_u32_e32 v206, v205, v176
	ds_read_b128 v[198:201], v206 offset:32768
	v_add_u32_e32 v207, v205, v175
	v_add_u32_e32 v208, v205, v173
	v_add_u32_e32 v205, v205, v171
	s_and_b32 s9, s64, 0x4000
	s_add_i32 s46, s9, 0
	v_add_u32_e32 v213, s46, v165
	s_andn2_b64 vcc, exec, s[0:1]
	s_waitcnt lgkmcnt(4)
	v_mfma_f32_32x32x16_bf16 v[80:95], v[214:217], v[112:115], v[64:79]
	ds_read_b128 v[214:217], v206 offset:36864
	v_exp_f32_e32 v209, v108
	s_waitcnt lgkmcnt(4)
	v_mfma_f32_32x32x16_bf16 v[80:95], v[218:221], v[116:119], v[80:95]
	ds_read_b128 v[218:221], v206 offset:40960
	v_exp_f32_e32 v210, v109
	s_waitcnt lgkmcnt(4)
	v_mfma_f32_32x32x16_bf16 v[80:95], v[246:249], v[120:123], v[80:95]
	ds_read_b128 v[246:249], v206 offset:45056
	v_exp_f32_e32 v206, v105
	s_waitcnt lgkmcnt(4)
	v_mfma_f32_32x32x16_bf16 v[80:95], v[236:239], v[124:127], v[80:95]
	ds_read_b128 v[236:239], v207 offset:32768
	v_exp_f32_e32 v211, v110
	s_waitcnt lgkmcnt(4)
	v_mfma_f32_32x32x16_bf16 v[48:63], v[198:201], v[148:151], v[48:63]
	ds_read_b128 v[198:201], v207 offset:36864
	v_exp_f32_e32 v212, v111
	s_waitcnt lgkmcnt(4)
	v_mfma_f32_32x32x16_bf16 v[32:47], v[214:217], v[148:151], v[32:47]
	ds_read_b128 v[214:217], v207 offset:40960
	s_waitcnt lgkmcnt(4)
	v_mfma_f32_32x32x16_bf16 v[16:31], v[218:221], v[148:151], v[16:31]
	ds_read_b128 v[218:221], v207 offset:45056
	v_exp_f32_e32 v207, v106
	s_waitcnt lgkmcnt(4)
	v_mfma_f32_32x32x16_bf16 v[0:15], v[246:249], v[148:151], v[0:15]
	ds_read_b128 v[246:249], v208 offset:32768
	s_waitcnt lgkmcnt(4)
	v_mfma_f32_32x32x16_bf16 v[48:63], v[236:239], v[144:147], v[48:63]
	ds_read_b128 v[236:239], v208 offset:36864
	s_waitcnt lgkmcnt(4)
	v_mfma_f32_32x32x16_bf16 v[32:47], v[198:201], v[144:147], v[32:47]
	ds_read_b128 v[198:201], v208 offset:40960
	s_waitcnt lgkmcnt(4)
	v_mfma_f32_32x32x16_bf16 v[16:31], v[214:217], v[144:147], v[16:31]
	ds_read_b128 v[214:217], v208 offset:45056
	v_exp_f32_e32 v208, v107
	s_waitcnt lgkmcnt(4)
	v_mfma_f32_32x32x16_bf16 v[0:15], v[218:221], v[144:147], v[0:15]
	ds_read_b128 v[218:221], v205 offset:32768
	s_waitcnt lgkmcnt(4)
	v_mfma_f32_32x32x16_bf16 v[48:63], v[246:249], v[140:143], v[48:63]
	ds_read_b128 v[246:249], v205 offset:36864
	s_waitcnt lgkmcnt(4)
	v_mfma_f32_32x32x16_bf16 v[32:47], v[236:239], v[140:143], v[32:47]
	ds_read_b128 v[236:239], v205 offset:40960
	s_waitcnt lgkmcnt(4)
	v_mfma_f32_32x32x16_bf16 v[16:31], v[198:201], v[140:143], v[16:31]
	ds_read_b128 v[148:151], v205 offset:45056
	v_exp_f32_e32 v205, v104
	v_exp_f32_e32 v198, v97
	v_exp_f32_e32 v199, v98
	s_waitcnt lgkmcnt(4)
	v_mfma_f32_32x32x16_bf16 v[0:15], v[214:217], v[140:143], v[0:15]
	ds_read_b128 v[214:217], v197
	v_exp_f32_e32 v197, v96
	v_exp_f32_e32 v200, v99
	v_exp_f32_e32 v201, v100
	s_waitcnt lgkmcnt(4)
	v_mfma_f32_32x32x16_bf16 v[48:63], v[218:221], v[136:139], v[48:63]
	ds_read_b128 v[218:221], v202
	v_exp_f32_e32 v202, v101
	v_add_f32_e32 v222, v197, v179
	v_add_f32_e32 v223, 0, v222
	v_add_f32_e32 v222, v198, v180
	v_add_f32_e32 v223, v222, v223
	v_add_f32_e32 v222, v199, v181
	v_add_f32_e32 v223, v222, v223
	s_waitcnt lgkmcnt(4)
	v_mfma_f32_32x32x16_bf16 v[32:47], v[246:249], v[136:139], v[32:47]
	ds_read_b128 v[246:249], v203
	v_exp_f32_e32 v203, v102
	v_add_f32_e32 v222, v200, v182
	v_add_f32_e32 v223, v222, v223
	v_add_f32_e32 v222, v201, v183
	v_add_f32_e32 v223, v222, v223
	v_add_f32_e32 v222, v202, v184
	v_add_f32_e32 v223, v222, v223
	s_waitcnt lgkmcnt(4)
	v_mfma_f32_32x32x16_bf16 v[16:31], v[236:239], v[136:139], v[16:31]
	ds_read_b128 v[236:239], v204
	v_exp_f32_e32 v204, v103
	v_add_f32_e32 v222, v203, v185
	v_add_f32_e32 v223, v222, v223
	s_waitcnt lgkmcnt(4)
	v_mfma_f32_32x32x16_bf16 v[0:15], v[148:151], v[136:139], v[0:15]
	v_add_f32_e32 v222, v204, v186
	v_add_f32_e32 v223, v222, v223
	v_cvt_pk_bf16_f32 v148, v197, v198
	v_cvt_pk_bf16_f32 v149, v199, v200
	v_cvt_pk_bf16_f32 v150, v201, v202
	v_cvt_pk_bf16_f32 v151, v203, v204
	v_cvt_pk_bf16_f32 v140, v179, v180
	v_cvt_pk_bf16_f32 v141, v181, v182
	v_cvt_pk_bf16_f32 v142, v183, v184
	s_waitcnt lgkmcnt(3)
	v_mfma_f32_32x32x16_bf16 v[96:111], v[214:217], v[112:115], v[64:79]
	v_add_f32_e32 v222, v205, v187
	v_add_f32_e32 v223, v222, v223
	v_add_f32_e32 v222, v206, v188
	v_add_f32_e32 v223, v222, v223
	v_add_f32_e32 v222, v207, v189
	v_add_f32_e32 v223, v222, v223
	v_add_f32_e32 v222, v208, v190
	v_add_f32_e32 v223, v222, v223
	v_add_u32_e32 v214, v213, v172
	v_cvt_pk_bf16_f32 v143, v185, v186
	v_cvt_pk_bf16_f32 v144, v205, v206
	v_cvt_pk_bf16_f32 v145, v207, v208
	v_cvt_pk_bf16_f32 v146, v209, v210
	v_cvt_pk_bf16_f32 v147, v211, v212
	v_cvt_pk_bf16_f32 v136, v187, v188
	s_waitcnt lgkmcnt(2)
	v_mfma_f32_32x32x16_bf16 v[96:111], v[218:221], v[116:119], v[96:111]
	v_add_f32_e32 v222, v209, v191
	v_add_f32_e32 v223, v222, v223
	v_add_f32_e32 v222, v210, v194
	v_add_f32_e32 v223, v222, v223
	v_add_f32_e32 v222, v211, v195
	v_add_f32_e32 v223, v222, v223
	v_add_f32_e32 v222, v212, v196
	v_add_f32_e32 v223, v222, v223
	v_add_f32_e32 v168, v168, v223
	v_cvt_pk_bf16_f32 v137, v189, v190
	v_cvt_pk_bf16_f32 v138, v191, v194
	v_cvt_pk_bf16_f32 v139, v195, v196
	s_waitcnt vmcnt(1)
	ds_write_b64 v214, v[152:153] offset:32768
	v_add_u32_e32 v152, v213, v169
	s_waitcnt vmcnt(0)
	ds_write_b64 v214, v[156:157] offset:40960
	ds_write2st64_b64 v152, v[154:155], v[158:159] offset0:64 offset1:80
	s_waitcnt lgkmcnt(4)
	v_mfma_f32_32x32x16_bf16 v[96:111], v[246:249], v[120:123], v[96:111]
	s_waitcnt lgkmcnt(3)
	v_mfma_f32_32x32x16_bf16 v[96:111], v[236:239], v[124:127], v[96:111]
	s_cbranch_vccnz .LBB0_212
	v_add_u32_e32 v152, s46, v170
	ds_write_b128 v152, v[128:131]
	ds_write_b128 v152, v[132:135] offset:8192

.Lattn_rot_nok:
	v_exp_f32_e32 v179, v80
	v_exp_f32_e32 v180, v81
	v_exp_f32_e32 v181, v82
	v_exp_f32_e32 v182, v83
	v_exp_f32_e32 v183, v84
	v_exp_f32_e32 v184, v85
	v_exp_f32_e32 v185, v86
	v_exp_f32_e32 v186, v87
	v_exp_f32_e32 v187, v88
	v_exp_f32_e32 v188, v89
	v_exp_f32_e32 v189, v90
	v_exp_f32_e32 v190, v91
	v_exp_f32_e32 v191, v92
	v_exp_f32_e32 v194, v93
	v_exp_f32_e32 v195, v94
	v_exp_f32_e32 v196, v95
	s_waitcnt lgkmcnt(0)
	s_barrier
	s_mov_b32 s64, s71
	s_branch .LBB0_210
